# best + NA: lgkmcnt wait ladders merged (29 waits removed, checker-guarded)
# baseline (speedup 1.0000x reference)
.LBB0_307:
	s_add_i32 s16, s47, s49
	s_add_i32 s51, s16, -2
	s_cmp_ge_u32 s51, s24
	s_cselect_b64 s[16:17], -1, 0
	s_cmp_lt_u32 s51, s31
	s_cselect_b64 s[52:53], -1, 0
	s_and_b64 s[16:17], s[16:17], s[52:53]
	s_andn2_b64 vcc, exec, s[16:17]
	s_cbranch_vccnz .LBB0_309
	v_add_u32_e32 v85, v118, v107
	ds_read_b128 v[194:197], v85
	ds_read_b128 v[202:205], v85 offset:2048
	v_add_u32_e32 v193, v118, v108
	ds_read_b128 v[198:201], v193
	ds_read_b128 v[206:209], v193 offset:2048
	s_waitcnt lgkmcnt(1)
	v_mfma_f32_16x16x32_bf16 v[194:197], v[194:197], v[20:23], 0
	v_mfma_f32_16x16x32_bf16 v[194:197], v[198:201], v[24:27], v[194:197]
	ds_read_b32 v198, v192
	ds_read_b32 v199, v191
	ds_read_b32 v200, v190
	ds_read_b32 v210, v189
	ds_read_b32 v211, v188
	ds_read_b32 v85, v187
	ds_read_b32 v212, v186
	ds_read_b32 v193, v185
	s_waitcnt lgkmcnt(5)
	v_add_f32_e32 v194, v194, v198
	v_exp_f32_e32 v214, v194
	v_add_f32_e32 v194, v195, v199
	v_exp_f32_e32 v222, v194
	v_add_f32_e32 v194, v196, v200
	v_mfma_f32_16x16x32_bf16 v[198:201], v[202:205], v[20:23], 0
	v_exp_f32_e32 v224, v194
	s_waitcnt lgkmcnt(4)
	v_add_f32_e32 v194, v197, v210
	v_exp_f32_e32 v226, v194
	v_mfma_f32_16x16x32_bf16 v[194:197], v[206:209], v[24:27], v[198:201]
	v_add_u32_e32 v215, 0, v178
	s_nop 1
	v_cvt_pk_bf16_f32 v198, v214, v222
	v_cvt_pk_bf16_f32 v199, v224, v226
	s_waitcnt lgkmcnt(0)
	s_nop 1
	v_add_f32_e32 v85, v195, v85
	v_exp_f32_e32 v230, v85
	v_add_f32_e32 v85, v196, v212
	v_add_f32_e32 v194, v194, v211
	v_exp_f32_e32 v232, v85
	v_add_f32_e32 v85, v197, v193
	v_add_u32_e32 v193, v119, v111
	v_exp_f32_e32 v228, v194
	ds_read_b64_tr_b16 v[194:195], v193 offset:8192
	ds_read_b64_tr_b16 v[196:197], v193 offset:10240
	v_exp_f32_e32 v234, v85
	v_add_u32_e32 v85, v119, v112
	v_cvt_pk_bf16_f32 v200, v228, v230
	ds_read_b64_tr_b16 v[202:203], v85 offset:8192
	ds_read_b64_tr_b16 v[204:205], v85 offset:10240
	v_cvt_pk_bf16_f32 v201, v232, v234
	v_add_u32_e32 v85, v119, v113
	v_add_u32_e32 v193, v120, v108
	s_waitcnt lgkmcnt(2)
	v_mfma_f32_16x16x32_bf16 v[76:79], v[194:197], v[198:201], v[76:79]
	ds_read_b64_tr_b16 v[194:195], v85 offset:8192
	ds_read_b64_tr_b16 v[196:197], v85 offset:10240
	v_add_u32_e32 v85, v119, v114
	s_waitcnt lgkmcnt(2)
	v_mfma_f32_16x16x32_bf16 v[64:67], v[202:205], v[198:201], v[64:67]
	ds_read_b64_tr_b16 v[202:203], v85 offset:8192
	ds_read_b64_tr_b16 v[204:205], v85 offset:10240
	v_add_u32_e32 v85, v120, v107
	ds_read_b128 v[206:209], v85 offset:2048
	s_waitcnt lgkmcnt(3)
	v_mfma_f32_16x16x32_bf16 v[72:75], v[194:197], v[198:201], v[72:75]
	ds_read_b128 v[194:197], v85
	ds_read_b128 v[210:213], v193
	ds_read_b128 v[218:221], v193 offset:2048
	s_waitcnt lgkmcnt(1)
	v_mfma_f32_16x16x32_bf16 v[194:197], v[194:197], v[36:39], 0
	v_mfma_f32_16x16x32_bf16 v[194:197], v[210:213], v[40:43], v[194:197]
	ds_read_b32 v85, v184
	ds_read_b32 v193, v183
	ds_read_b32 v210, v182
	ds_read_b32 v211, v181
	ds_read_b32 v212, v180
	ds_read_b32 v213, v179
	ds_read_b32 v233, v215
	ds_read_b32 v217, v177
	s_waitcnt lgkmcnt(4)
	v_add_f32_e32 v85, v194, v85
	v_exp_f32_e32 v215, v85
	v_add_f32_e32 v85, v195, v193
	v_exp_f32_e32 v223, v85
	v_mfma_f32_16x16x32_bf16 v[68:71], v[202:205], v[198:201], v[68:71]
	v_add_f32_e64 v194, v214, 0
	v_add_f32_e64 v195, v215, 0
	v_add_f32_e32 v85, v196, v210
	v_pk_add_f32 v[202:203], v[194:195], v[222:223]
	v_mfma_f32_16x16x32_bf16 v[198:201], v[206:209], v[36:39], 0
	v_exp_f32_e32 v225, v85
	v_add_f32_e32 v85, v197, v211
	v_exp_f32_e32 v227, v85
	v_mfma_f32_16x16x32_bf16 v[194:197], v[218:221], v[40:43], v[198:201]
	v_add_f32_e64 v210, v202, v224
	v_add_f32_e64 v211, v203, v225
	s_waitcnt lgkmcnt(0)
	s_nop 4
	v_add_f32_e32 v85, v194, v212
	v_exp_f32_e32 v229, v85
	v_add_f32_e32 v85, v195, v213
	v_exp_f32_e32 v231, v85
	v_add_f32_e32 v85, v196, v233
	v_exp_f32_e32 v233, v85
	v_add_f32_e32 v85, v197, v217
	v_exp_f32_e32 v235, v85
	v_add_u32_e32 v85, v121, v111
	ds_read_b64_tr_b16 v[198:199], v85 offset:8192
	ds_read_b64_tr_b16 v[200:201], v85 offset:10240
	v_add_u32_e32 v85, v121, v112
	ds_read_b64_tr_b16 v[202:203], v85 offset:8192
	ds_read_b64_tr_b16 v[204:205], v85 offset:10240
	v_add_u32_e32 v85, v121, v113
	v_cvt_pk_bf16_f32 v194, v215, v223
	v_cvt_pk_bf16_f32 v195, v225, v227
	v_cvt_pk_bf16_f32 v196, v229, v231
	v_cvt_pk_bf16_f32 v197, v233, v235
	ds_read_b64_tr_b16 v[206:207], v85 offset:8192
	ds_read_b64_tr_b16 v[208:209], v85 offset:10240
	v_add_u32_e32 v85, v121, v114
	s_waitcnt lgkmcnt(4)
	v_mfma_f32_16x16x32_bf16 v[60:63], v[198:201], v[194:197], v[60:63]
	ds_read_b64_tr_b16 v[198:199], v85 offset:8192
	ds_read_b64_tr_b16 v[200:201], v85 offset:10240
	s_waitcnt lgkmcnt(0)
	v_mfma_f32_16x16x32_bf16 v[56:59], v[202:205], v[194:197], v[56:59]
	v_add_f32_e64 v202, v210, v226
	v_add_f32_e64 v203, v211, v227
	v_pk_add_f32 v[202:203], v[202:203], v[228:229]
	v_mfma_f32_16x16x32_bf16 v[52:55], v[206:209], v[194:197], v[52:55]
	v_add_f32_e64 v202, v202, v230
	v_add_f32_e64 v203, v203, v231
	v_pk_add_f32 v[202:203], v[202:203], v[232:233]
	v_mfma_f32_16x16x32_bf16 v[44:47], v[198:201], v[194:197], v[44:47]
	v_add_f32_e64 v202, v202, v234
	v_add_f32_e64 v203, v203, v235
	v_pk_add_f32 v[102:103], v[202:203], v[102:103]

.LBB0_314:
	s_add_i32 s16, s47, s49
	s_add_i32 s51, s16, -1
	s_cmp_ge_u32 s51, s24
	s_cselect_b64 s[16:17], -1, 0
	s_cmp_lt_u32 s51, s31
	s_cselect_b64 s[52:53], -1, 0
	s_and_b64 s[16:17], s[16:17], s[52:53]
	s_andn2_b64 vcc, exec, s[16:17]
	s_cbranch_vccnz .LBB0_316
	v_add_u32_e32 v85, v118, v107
	ds_read_b128 v[194:197], v85 offset:32768
	ds_read_b128 v[202:205], v85 offset:34816
	v_add_u32_e32 v193, v118, v108
	ds_read_b128 v[198:201], v193 offset:32768
	ds_read_b128 v[206:209], v193 offset:34816
	v_add_u32_e32 v210, s48, v176
	v_add_u32_e32 v211, s48, v175
	v_add_u32_e32 v213, s48, v173
	v_add_u32_e32 v85, s48, v171
	s_waitcnt lgkmcnt(1)
	v_mfma_f32_16x16x32_bf16 v[194:197], v[194:197], v[20:23], 0
	v_add_u32_e32 v215, s48, v170
	v_add_u32_e32 v193, s48, v169
	v_add_u32_e32 v212, s48, v174
	v_mfma_f32_16x16x32_bf16 v[194:197], v[198:201], v[24:27], v[194:197]
	v_add_u32_e32 v214, s48, v172
	ds_read_b32 v198, v210
	ds_read_b32 v199, v211
	ds_read_b32 v200, v212
	ds_read_b32 v211, v213
	ds_read_b32 v213, v214
	ds_read_b32 v85, v85
	ds_read_b32 v215, v215
	ds_read_b32 v193, v193
	s_waitcnt lgkmcnt(4)
	v_add_f32_e32 v194, v194, v198
	v_exp_f32_e32 v210, v194
	v_add_f32_e32 v194, v195, v199
	v_exp_f32_e32 v212, v194
	v_add_f32_e32 v194, v196, v200
	v_mfma_f32_16x16x32_bf16 v[198:201], v[202:205], v[20:23], 0
	v_exp_f32_e32 v214, v194
	v_add_f32_e32 v194, v197, v211
	v_exp_f32_e32 v218, v194
	v_mfma_f32_16x16x32_bf16 v[194:197], v[206:209], v[24:27], v[198:201]
	v_cvt_pk_bf16_f32 v202, v210, v212
	v_add_u32_e32 v211, s48, v162
	v_cvt_pk_bf16_f32 v203, v214, v218
	s_waitcnt lgkmcnt(0)
	s_nop 3
	v_add_f32_e32 v85, v195, v85
	v_exp_f32_e32 v222, v85
	v_add_f32_e32 v85, v196, v215
	v_add_f32_e32 v194, v194, v213
	v_exp_f32_e32 v224, v85
	v_add_f32_e32 v85, v197, v193
	v_add_u32_e32 v193, v119, v111
	v_exp_f32_e32 v220, v194
	ds_read_b64_tr_b16 v[194:195], v193 offset:40960
	ds_read_b64_tr_b16 v[196:197], v193 offset:43008
	v_exp_f32_e32 v226, v85
	v_add_u32_e32 v85, v119, v112
	ds_read_b64_tr_b16 v[198:199], v85 offset:40960
	ds_read_b64_tr_b16 v[200:201], v85 offset:43008
	v_cvt_pk_bf16_f32 v204, v220, v222
	v_cvt_pk_bf16_f32 v205, v224, v226
	v_add_u32_e32 v85, v119, v113
	v_add_u32_e32 v193, v120, v108
	s_waitcnt lgkmcnt(2)
	v_mfma_f32_16x16x32_bf16 v[76:79], v[194:197], v[202:205], v[76:79]
	ds_read_b64_tr_b16 v[194:195], v85 offset:40960
	ds_read_b64_tr_b16 v[196:197], v85 offset:43008
	v_add_u32_e32 v85, v119, v114
	v_add_u32_e32 v213, s48, v161
	s_waitcnt lgkmcnt(2)
	v_mfma_f32_16x16x32_bf16 v[64:67], v[198:201], v[202:205], v[64:67]
	ds_read_b64_tr_b16 v[198:199], v85 offset:40960
	ds_read_b64_tr_b16 v[200:201], v85 offset:43008
	v_add_u32_e32 v85, v120, v107
	s_waitcnt lgkmcnt(2)
	v_mfma_f32_16x16x32_bf16 v[72:75], v[194:197], v[202:205], v[72:75]
	ds_read_b128 v[194:197], v85 offset:32768
	s_waitcnt lgkmcnt(1)
	v_mfma_f32_16x16x32_bf16 v[68:71], v[198:201], v[202:205], v[68:71]
	ds_read_b128 v[198:201], v85 offset:34816
	ds_read_b128 v[202:205], v193 offset:32768
	ds_read_b128 v[206:209], v193 offset:34816
	v_add_u32_e32 v85, s48, v168
	s_waitcnt lgkmcnt(1)
	v_mfma_f32_16x16x32_bf16 v[194:197], v[194:197], v[36:39], 0
	v_add_u32_e32 v193, s48, v167
	v_mfma_f32_16x16x32_bf16 v[194:197], v[202:205], v[40:43], v[194:197]
	v_add_u32_e32 v202, s48, v166
	v_add_u32_e32 v203, s48, v165
	v_add_u32_e32 v204, s48, v164
	v_add_u32_e32 v205, s48, v163
	ds_read_b32 v85, v85
	ds_read_b32 v193, v193
	ds_read_b32 v202, v202
	ds_read_b32 v203, v203
	ds_read_b32 v204, v204
	ds_read_b32 v205, v205
	ds_read_b32 v217, v211
	ds_read_b32 v227, v213
	v_mfma_f32_16x16x32_bf16 v[198:201], v[198:201], v[36:39], 0
	s_waitcnt lgkmcnt(4)
	v_add_f32_e32 v85, v194, v85
	v_exp_f32_e32 v211, v85
	v_add_f32_e32 v85, v195, v193
	v_exp_f32_e32 v213, v85
	v_add_f32_e32 v85, v196, v202
	v_exp_f32_e32 v215, v85
	v_add_f32_e32 v85, v197, v203
	v_mfma_f32_16x16x32_bf16 v[194:197], v[206:209], v[40:43], v[198:201]
	v_exp_f32_e32 v219, v85
	s_waitcnt lgkmcnt(0)
	s_nop 5
	v_add_f32_e32 v85, v194, v204
	v_exp_f32_e32 v221, v85
	v_add_f32_e32 v85, v195, v205
	v_exp_f32_e32 v223, v85
	v_add_f32_e32 v85, v196, v217
	v_exp_f32_e32 v225, v85
	v_add_f32_e32 v85, v197, v227
	v_exp_f32_e32 v227, v85
	v_add_u32_e32 v85, v121, v111
	ds_read_b64_tr_b16 v[198:199], v85 offset:40960
	ds_read_b64_tr_b16 v[200:201], v85 offset:43008
	v_pk_add_f32 v[194:195], v[210:211], 0 op_sel_hi:[1,0]
	v_add_u32_e32 v85, v121, v112
	v_pk_add_f32 v[194:195], v[194:195], v[212:213]
	ds_read_b64_tr_b16 v[202:203], v85 offset:40960
	ds_read_b64_tr_b16 v[204:205], v85 offset:43008
	v_add_u32_e32 v85, v121, v113
	v_pk_add_f32 v[228:229], v[194:195], v[214:215]
	v_cvt_pk_bf16_f32 v194, v211, v213
	v_cvt_pk_bf16_f32 v195, v215, v219
	v_cvt_pk_bf16_f32 v196, v221, v223
	v_cvt_pk_bf16_f32 v197, v225, v227
	ds_read_b64_tr_b16 v[206:207], v85 offset:40960
	ds_read_b64_tr_b16 v[208:209], v85 offset:43008
	v_add_u32_e32 v85, v121, v114
	s_waitcnt lgkmcnt(4)
	v_mfma_f32_16x16x32_bf16 v[60:63], v[198:201], v[194:197], v[60:63]
	ds_read_b64_tr_b16 v[198:199], v85 offset:40960
	ds_read_b64_tr_b16 v[200:201], v85 offset:43008
	s_waitcnt lgkmcnt(0)
	v_mfma_f32_16x16x32_bf16 v[56:59], v[202:205], v[194:197], v[56:59]
	v_add_f32_e64 v202, v228, v218
	v_add_f32_e64 v203, v229, v219
	v_pk_add_f32 v[202:203], v[202:203], v[220:221]
	v_mfma_f32_16x16x32_bf16 v[52:55], v[206:209], v[194:197], v[52:55]
	v_add_f32_e64 v202, v202, v222
	v_add_f32_e64 v203, v203, v223
	v_pk_add_f32 v[202:203], v[202:203], v[224:225]
	v_mfma_f32_16x16x32_bf16 v[44:47], v[198:201], v[194:197], v[44:47]
	v_add_f32_e64 v202, v202, v226
	v_add_f32_e64 v203, v203, v227
	v_pk_add_f32 v[102:103], v[202:203], v[102:103]
